# first grid barrier: the 16 per-XCD registration counters are loaded together (one round trip instead of 16 dependent ones)
# baseline (speedup 1.0000x reference)
.LBB0_584:
	s_mov_b64 s[4:5], -1
	v_readlane_b32 s2, v252, 11
	v_readlane_b32 s3, v252, 12
	s_nop 4
	global_load_dword v0, v9, s[2:3] sc1
	v_readlane_b32 s2, v252, 13
	v_readlane_b32 s3, v252, 14
	s_nop 4
	global_load_dword v1, v9, s[2:3] sc1
	v_readlane_b32 s2, v252, 15
	v_readlane_b32 s3, v252, 16
	s_nop 4
	global_load_dword v2, v9, s[2:3] sc1
	v_readlane_b32 s2, v252, 17
	v_readlane_b32 s3, v252, 18
	s_nop 4
	global_load_dword v3, v9, s[2:3] sc1
	v_readlane_b32 s2, v252, 19
	v_readlane_b32 s3, v252, 20
	s_nop 4
	global_load_dword v4, v9, s[2:3] sc1
	v_readlane_b32 s2, v252, 21
	v_readlane_b32 s3, v252, 22
	s_nop 4
	global_load_dword v5, v9, s[2:3] sc1
	v_readlane_b32 s2, v252, 23
	v_readlane_b32 s3, v252, 24
	s_nop 4
	global_load_dword v6, v9, s[2:3] sc1
	v_readlane_b32 s2, v252, 25
	v_readlane_b32 s3, v252, 26
	s_nop 4
	global_load_dword v7, v9, s[2:3] sc1
	v_readlane_b32 s2, v252, 27
	v_readlane_b32 s3, v252, 28
	s_nop 4
	global_load_dword v8, v9, s[2:3] sc1
	v_readlane_b32 s2, v252, 29
	v_readlane_b32 s3, v252, 30
	s_nop 4
	global_load_dword v10, v9, s[2:3] sc1
	v_readlane_b32 s2, v252, 31
	v_readlane_b32 s3, v252, 32
	s_nop 4
	global_load_dword v11, v9, s[2:3] sc1
	v_readlane_b32 s2, v252, 33
	v_readlane_b32 s3, v252, 34
	s_nop 4
	global_load_dword v12, v9, s[2:3] sc1
	v_readlane_b32 s2, v252, 35
	v_readlane_b32 s3, v252, 36
	s_nop 4
	global_load_dword v13, v9, s[2:3] sc1
	v_readlane_b32 s2, v252, 37
	v_readlane_b32 s3, v252, 38
	s_nop 4
	global_load_dword v14, v9, s[2:3] sc1
	v_readlane_b32 s2, v252, 39
	v_readlane_b32 s3, v252, 40
	s_nop 4
	global_load_dword v15, v9, s[2:3] sc1
	v_readlane_b32 s2, v252, 41
	v_readlane_b32 s3, v252, 42
	s_nop 4
	global_load_dword v16, v9, s[2:3] sc1
	s_mov_b64 s[2:3], -1
	s_waitcnt vmcnt(0)
	v_add_u32_e32 v17, v1, v0
	v_add_u32_e32 v17, v17, v2
	v_add_u32_e32 v17, v17, v3
	v_add_u32_e32 v17, v17, v4
	v_add_u32_e32 v17, v17, v5
	v_add_u32_e32 v17, v17, v6
	v_add_u32_e32 v17, v17, v7
	v_add_u32_e32 v17, v17, v8
	v_add_u32_e32 v17, v17, v10
	v_add_u32_e32 v17, v17, v11
	v_add_u32_e32 v17, v17, v12
	v_add_u32_e32 v17, v17, v13
	v_add_u32_e32 v17, v17, v14
	v_add_u32_e32 v17, v17, v15
	v_add_u32_e32 v17, v17, v16
	v_cmp_eq_u32_e32 vcc, s18, v17
	s_cbranch_vccnz .LBB0_583
	s_and_b32 s2, s19, 0xff
	s_cmp_eq_u32 s2, 0
	s_mov_b64 s[2:3], -1
	s_mov_b64 s[6:7], -1
	s_sleep 1
	s_cbranch_scc0 .LBB0_588
	v_readlane_b32 s2, v252, 9
	v_readlane_b32 s3, v252, 10
	s_nop 4
	global_load_dword v17, v9, s[2:3] sc1
	s_waitcnt vmcnt(0)
	v_cmp_eq_u32_e32 vcc, 0, v17
	s_cbranch_vccnz .LBB0_590
	s_mov_b64 s[6:7], 0
	s_mov_b64 s[2:3], -1
